# merge loop: the 16 ds_bpermute + lgkmcnt(0) butterfly steps per iteration replaced by DPP adds (quad_perm / row_half_mirror / row_mirror), identical sums
# baseline (speedup 1.0000x reference)
.LBB0_495:
	s_nop 0
	v_lshl_add_u64 v[8:9], s[34:35], 0, v[130:131]
	v_add_co_u32_e32 v8, vcc, s11, v8
	s_addk_i32 s10, 0x2000
	s_nop 0
	v_addc_co_u32_e32 v9, vcc, 0, v9, vcc
	global_load_dwordx4 v[84:87], v[8:9], off
	global_load_dwordx4 v[80:83], v[8:9], off offset:256
	v_lshl_add_u64 v[8:9], s[34:35], 0, v[128:129]
	v_add_co_u32_e32 v10, vcc, s12, v8
	v_lshl_add_u64 v[128:129], v[128:129], 0, s[6:7]
	s_nop 0
	v_addc_co_u32_e32 v11, vcc, 0, v9, vcc
	global_load_dword v151, v[10:11], off
	v_add_co_u32_e32 v10, vcc, s13, v8
	v_lshl_add_u64 v[130:131], v[130:131], 0, s[8:9]
	s_nop 0
	v_addc_co_u32_e32 v11, vcc, 0, v9, vcc
	v_add_co_u32_e32 v8, vcc, s16, v8
	global_load_dword v152, v[10:11], off
	s_nop 0
	v_addc_co_u32_e32 v9, vcc, 0, v9, vcc
	global_load_dword v153, v[8:9], off
	v_lshl_add_u64 v[8:9], s[34:35], 0, v[126:127]
	v_add_co_u32_e32 v10, vcc, s17, v8
	v_lshl_add_u64 v[126:127], v[126:127], 0, s[4:5]
	s_nop 0
	v_addc_co_u32_e32 v11, vcc, 0, v9, vcc
	global_load_dwordx4 v[72:75], v[10:11], off
	v_add_co_u32_e32 v10, vcc, s18, v8
	s_cmpk_lt_i32 s10, 0x2000
	s_nop 0
	v_addc_co_u32_e32 v11, vcc, 0, v9, vcc
	v_add_co_u32_e32 v8, vcc, s19, v8
	global_load_dwordx4 v[76:79], v[10:11], off
	s_nop 0
	v_addc_co_u32_e32 v9, vcc, 0, v9, vcc
	global_load_dwordx4 v[68:71], v[8:9], off
	v_lshl_add_u64 v[8:9], s[34:35], 0, v[116:117]
	v_add_co_u32_e32 v8, vcc, s11, v8
	v_lshl_add_u64 v[116:117], v[116:117], 0, s[8:9]
	s_nop 0
	v_addc_co_u32_e32 v9, vcc, 0, v9, vcc
	global_load_dwordx4 v[64:67], v[8:9], off
	global_load_dwordx4 v[60:63], v[8:9], off offset:256
	v_lshl_add_u64 v[8:9], s[34:35], 0, v[114:115]
	v_add_co_u32_e32 v10, vcc, s12, v8
	v_lshl_add_u64 v[114:115], v[114:115], 0, s[6:7]
	s_nop 0
	v_addc_co_u32_e32 v11, vcc, 0, v9, vcc
	global_load_dword v148, v[10:11], off
	v_add_co_u32_e32 v10, vcc, s13, v8
	s_waitcnt vmcnt(10)
	v_lshlrev_b32_e32 v155, 16, v85
	v_addc_co_u32_e32 v11, vcc, 0, v9, vcc
	v_add_co_u32_e32 v8, vcc, s16, v8
	global_load_dword v149, v[10:11], off
	s_nop 0
	v_addc_co_u32_e32 v9, vcc, 0, v9, vcc
	global_load_dword v150, v[8:9], off
	v_lshl_add_u64 v[8:9], s[34:35], 0, v[112:113]
	v_add_co_u32_e32 v10, vcc, s17, v8
	v_lshlrev_b32_e32 v154, 16, v84
	s_nop 0
	v_addc_co_u32_e32 v11, vcc, 0, v9, vcc
	global_load_dwordx4 v[52:55], v[10:11], off
	v_add_co_u32_e32 v10, vcc, s18, v8
	s_waitcnt vmcnt(12)
	v_lshlrev_b32_e32 v157, 16, v81
	v_addc_co_u32_e32 v11, vcc, 0, v9, vcc
	v_add_co_u32_e32 v8, vcc, s19, v8
	v_lshlrev_b32_e32 v156, 16, v80
	s_nop 0
	v_addc_co_u32_e32 v9, vcc, 0, v9, vcc
	v_and_b32_e32 v85, 0xffff0000, v85
	v_and_b32_e32 v84, 0xffff0000, v84
	v_and_b32_e32 v81, 0xffff0000, v81
	v_and_b32_e32 v80, 0xffff0000, v80
	global_load_dwordx4 v[56:59], v[10:11], off
	global_load_dwordx4 v[48:51], v[8:9], off
	v_lshl_add_u64 v[8:9], s[34:35], 0, v[106:107]
	v_pk_fma_f32 v[154:155], v[122:123], v[156:157], v[154:155] neg_lo:[1,0,0] neg_hi:[1,0,0]
	v_pk_fma_f32 v[80:81], v[122:123], v[80:81], v[84:85] neg_lo:[1,0,0] neg_hi:[1,0,0]
	v_add_co_u32_e32 v8, vcc, s11, v8
	v_pk_mul_f32 v[84:85], v[154:155], v[154:155]
	v_pk_mul_f32 v[156:157], v[80:81], v[80:81]
	v_lshlrev_b32_e32 v159, 16, v87
	v_lshlrev_b32_e32 v158, 16, v86
	v_lshlrev_b32_e32 v161, 16, v83
	v_lshlrev_b32_e32 v160, 16, v82
	v_and_b32_e32 v87, 0xffff0000, v87
	v_and_b32_e32 v86, 0xffff0000, v86
	v_and_b32_e32 v83, 0xffff0000, v83
	v_and_b32_e32 v82, 0xffff0000, v82
	v_addc_co_u32_e32 v9, vcc, 0, v9, vcc
	v_pk_fma_f32 v[158:159], v[122:123], v[160:161], v[158:159] neg_lo:[1,0,0] neg_hi:[1,0,0]
	v_pk_fma_f32 v[82:83], v[122:123], v[82:83], v[86:87] neg_lo:[1,0,0] neg_hi:[1,0,0]
	v_add_f32_e32 v84, v84, v156
	global_load_dwordx4 v[44:47], v[8:9], off
	global_load_dwordx4 v[40:43], v[8:9], off offset:256
	v_lshl_add_u64 v[8:9], s[34:35], 0, v[104:105]
	v_mov_b32_e32 v86, v82
	v_mov_b32_e32 v87, v158
	v_add_f32_e32 v84, v85, v84
	v_add_co_u32_e32 v10, vcc, s12, v8
	v_pk_mul_f32 v[86:87], v[86:87], v[86:87]
	v_add_f32_e32 v84, v157, v84
	v_addc_co_u32_e32 v11, vcc, 0, v9, vcc
	v_mov_b32_e32 v160, v83
	v_mov_b32_e32 v161, v159
	v_add_f32_e32 v84, v87, v84
	global_load_dword v145, v[10:11], off
	v_add_co_u32_e32 v10, vcc, s13, v8
	v_pk_mul_f32 v[160:161], v[160:161], v[160:161]
	v_add_f32_e32 v84, v86, v84
	v_addc_co_u32_e32 v11, vcc, 0, v9, vcc
	v_add_f32_e32 v84, v161, v84
	v_add_co_u32_e32 v8, vcc, s16, v8
	v_add_f32_e32 v84, v160, v84
	s_nop 0
	v_addc_co_u32_e32 v9, vcc, 0, v9, vcc
	global_load_dword v146, v[10:11], off
	global_load_dword v147, v[8:9], off
	v_lshl_add_u64 v[8:9], s[34:35], 0, v[102:103]
	v_add_co_u32_e32 v10, vcc, s17, v8
	s_waitcnt lgkmcnt(0)
	s_nop 1
	v_add_f32_dpp v84, v84, v84 quad_perm:[1,0,3,2] row_mask:0xf bank_mask:0xf
	v_addc_co_u32_e32 v11, vcc, 0, v9, vcc
	global_load_dwordx4 v[32:35], v[10:11], off
	v_add_co_u32_e32 v10, vcc, s18, v8
	s_nop 0
	v_addc_co_u32_e32 v11, vcc, 0, v9, vcc
	v_add_co_u32_e32 v8, vcc, s19, v8
	global_load_dwordx4 v[36:39], v[10:11], off
	s_nop 0
	v_addc_co_u32_e32 v9, vcc, 0, v9, vcc
	global_load_dwordx4 v[28:31], v[8:9], off
	v_lshl_add_u64 v[8:9], s[34:35], 0, v[94:95]
	v_add_co_u32_e32 v8, vcc, s11, v8
	s_waitcnt lgkmcnt(0)
	s_nop 1
	v_add_f32_dpp v84, v84, v84 quad_perm:[2,3,0,1] row_mask:0xf bank_mask:0xf
	v_addc_co_u32_e32 v9, vcc, 0, v9, vcc
	global_load_dwordx4 v[24:27], v[8:9], off
	global_load_dwordx4 v[20:23], v[8:9], off offset:256
	v_lshl_add_u64 v[8:9], s[34:35], 0, v[92:93]
	v_add_co_u32_e32 v10, vcc, s12, v8
	s_nop 0
	v_addc_co_u32_e32 v11, vcc, 0, v9, vcc
	global_load_dword v142, v[10:11], off
	v_add_co_u32_e32 v10, vcc, s13, v8
	s_waitcnt lgkmcnt(0)
	s_nop 1
	v_add_f32_dpp v84, v84, v84 row_half_mirror row_mask:0xf bank_mask:0xf
	v_addc_co_u32_e32 v11, vcc, 0, v9, vcc
	v_add_co_u32_e32 v8, vcc, s16, v8
	global_load_dword v143, v[10:11], off
	s_nop 0
	v_addc_co_u32_e32 v9, vcc, 0, v9, vcc
	global_load_dword v144, v[8:9], off
	v_lshl_add_u64 v[8:9], s[34:35], 0, v[90:91]
	v_add_co_u32_e32 v10, vcc, s17, v8
	v_lshl_add_u64 v[90:91], v[90:91], 0, s[4:5]
	s_nop 0
	v_addc_co_u32_e32 v11, vcc, 0, v9, vcc
	global_load_dwordx4 v[12:15], v[10:11], off
	v_add_co_u32_e32 v10, vcc, s18, v8
	s_waitcnt lgkmcnt(0)
	s_nop 1
	v_add_f32_dpp v84, v84, v84 row_mirror row_mask:0xf bank_mask:0xf
	v_addc_co_u32_e32 v11, vcc, 0, v9, vcc
	v_add_co_u32_e32 v8, vcc, s19, v8
	v_fmamk_f32 v84, v84, 0x3c000000, v140
	s_nop 0
	v_addc_co_u32_e32 v9, vcc, 0, v9, vcc
	v_cmp_gt_f32_e32 vcc, s21, v84
	v_mul_f32_e32 v85, 0x4f800000, v84
	global_load_dwordx4 v[16:19], v[10:11], off
	v_cndmask_b32_e32 v84, v84, v85, vcc
	v_sqrt_f32_e32 v85, v84
	global_load_dwordx4 v[8:11], v[8:9], off
	v_lshl_add_u64 v[92:93], v[92:93], 0, s[6:7]
	v_lshl_add_u64 v[94:95], v[94:95], 0, s[8:9]
	v_add_u32_e32 v86, -1, v85
	v_fma_f32 v87, -v86, v85, v84
	v_cmp_ge_f32_e64 s[0:1], 0, v87
	v_add_u32_e32 v87, 1, v85
	v_lshl_add_u64 v[102:103], v[102:103], 0, s[4:5]
	v_cndmask_b32_e64 v86, v85, v86, s[0:1]
	v_fma_f32 v85, -v87, v85, v84
	v_cmp_lt_f32_e64 s[0:1], 0, v85
	v_lshl_add_u64 v[104:105], v[104:105], 0, s[6:7]
	v_lshl_add_u64 v[106:107], v[106:107], 0, s[8:9]
	v_cndmask_b32_e64 v85, v86, v87, s[0:1]
	v_mul_f32_e32 v86, 0x37800000, v85
	v_cndmask_b32_e32 v85, v85, v86, vcc
	v_cmp_class_f32_e32 vcc, v84, v141
	v_lshl_add_u64 v[112:113], v[112:113], 0, s[4:5]
	s_nop 0
	v_cndmask_b32_e32 v84, v85, v84, vcc
	v_div_scale_f32 v85, s[0:1], v84, v84, s22
	v_rcp_f32_e32 v86, v85
	s_nop 0
	v_fma_f32 v87, -v85, v86, 1.0
	v_fmac_f32_e32 v86, v87, v86
	v_div_scale_f32 v87, vcc, s22, v84, s22
	v_mul_f32_e32 v156, v87, v86
	v_fma_f32 v157, -v85, v156, v87
	v_fmac_f32_e32 v156, v157, v86
	v_fma_f32 v85, -v85, v156, v87
	v_div_fmas_f32 v85, v85, v86, v156
	v_div_fixup_f32 v84, v85, v84, s22
	v_pk_mul_f32 v[82:83], v[82:83], v[84:85] op_sel_hi:[1,0]
	v_pk_mul_f32 v[86:87], v[154:155], v[84:85] op_sel_hi:[1,0]
	v_pk_mul_f32 v[82:83], v[4:5], v[82:83]
	v_pk_mul_f32 v[86:87], v[2:3], v[86:87]
	v_pk_mul_f32 v[80:81], v[80:81], v[84:85] op_sel_hi:[1,0]
	v_pk_mul_f32 v[154:155], v[158:159], v[84:85] op_sel_hi:[1,0]
	v_bfe_u32 v84, v83, 16, 1
	v_bfe_u32 v85, v82, 16, 1
	v_pk_mul_f32 v[80:81], v[124:125], v[80:81]
	v_add3_u32 v82, v82, v85, s23
	v_add3_u32 v83, v83, v84, s23
	v_cvt_pk_bf16_f32 v80, v86, v80
	v_cvt_pk_bf16_f32 v81, v87, v81
	v_pk_mul_f32 v[154:155], v[6:7], v[154:155]
	v_bfe_u32 v156, v154, 16, 1
	v_bfe_u32 v157, v155, 16, 1
	v_add3_u32 v155, v155, v157, s23
	v_add3_u32 v154, v154, v156, s23
	v_lshl_add_u64 v[84:85], v[100:101], 0, v[134:135]
	v_lshrrev_b32_e32 v86, 16, v154
	v_lshrrev_b32_e32 v87, 16, v155
	v_add_co_u32_e32 v84, vcc, s24, v84
	v_and_or_b32 v83, v83, s20, v87
	v_and_or_b32 v82, v82, s20, v86
	v_addc_co_u32_e32 v85, vcc, -1, v85, vcc
	global_store_dwordx4 v[84:85], v[80:83], off offset:-256 sc1
	v_lshl_add_u64 v[134:135], v[134:135], 0, s[8:9]
	s_waitcnt vmcnt(28)
	v_max3_f32 v80, v151, v152, v153
	v_sub_f32_e32 v81, v151, v80
	v_exp_f32_e32 v83, v81
	v_sub_f32_e32 v81, v152, v80
	v_exp_f32_e32 v82, v81
	v_sub_f32_e32 v80, v153, v80
	v_exp_f32_e32 v80, v80
	v_add_f32_e32 v81, v83, v82
	v_add_f32_e32 v81, v80, v81
	v_div_scale_f32 v84, s[0:1], v81, v81, 1.0
	v_rcp_f32_e32 v85, v84
	s_nop 0
	v_fma_f32 v86, -v84, v85, 1.0
	v_fmac_f32_e32 v85, v86, v85
	v_div_scale_f32 v86, vcc, 1.0, v81, 1.0
	v_mul_f32_e32 v87, v86, v85
	v_fma_f32 v151, -v84, v87, v86
	v_fmac_f32_e32 v87, v151, v85
	v_fma_f32 v84, -v84, v87, v86
	v_div_fmas_f32 v84, v84, v85, v87
	v_div_fixup_f32 v84, v84, v81, 1.0
	v_pk_mul_f32 v[82:83], v[82:83], v[84:85] op_sel_hi:[1,0]
	s_waitcnt vmcnt(26)
	v_lshlrev_b32_e32 v87, 16, v77
	v_lshlrev_b32_e32 v86, 16, v72
	v_mul_f32_e32 v80, v80, v84
	v_lshlrev_b32_e32 v85, 16, v73
	v_lshlrev_b32_e32 v84, 16, v76
	v_pk_mul_f32 v[86:87], v[82:83], v[86:87] op_sel:[1,0] op_sel_hi:[0,1]
	v_pk_fma_f32 v[84:85], v[82:83], v[84:85], v[86:87]
	s_waitcnt vmcnt(25)
	v_lshlrev_b32_e32 v87, 16, v69
	v_lshlrev_b32_e32 v86, 16, v68
	v_pk_fma_f32 v[84:85], v[80:81], v[86:87], v[84:85] op_sel_hi:[0,1,1]
	v_and_b32_e32 v87, 0xffff0000, v73
	v_and_b32_e32 v73, 0xffff0000, v77
	v_and_b32_e32 v72, 0xffff0000, v72
	v_and_b32_e32 v86, 0xffff0000, v76
	v_pk_mul_f32 v[72:73], v[82:83], v[72:73] op_sel:[1,0] op_sel_hi:[0,1]
	v_pk_fma_f32 v[72:73], v[82:83], v[86:87], v[72:73]
	v_and_b32_e32 v69, 0xffff0000, v69
	v_and_b32_e32 v68, 0xffff0000, v68
	v_lshlrev_b32_e32 v77, 16, v79
	v_lshlrev_b32_e32 v76, 16, v74
	v_pk_fma_f32 v[68:69], v[80:81], v[68:69], v[72:73] op_sel_hi:[0,1,1]
	v_lshlrev_b32_e32 v73, 16, v75
	v_lshlrev_b32_e32 v72, 16, v78
	v_pk_mul_f32 v[76:77], v[82:83], v[76:77] op_sel:[1,0] op_sel_hi:[0,1]
	v_pk_fma_f32 v[72:73], v[82:83], v[72:73], v[76:77]
	v_lshlrev_b32_e32 v77, 16, v71
	v_lshlrev_b32_e32 v76, 16, v70
	v_pk_fma_f32 v[72:73], v[80:81], v[76:77], v[72:73] op_sel_hi:[0,1,1]
	v_and_b32_e32 v77, 0xffff0000, v75
	v_and_b32_e32 v75, 0xffff0000, v79
	v_and_b32_e32 v74, 0xffff0000, v74
	v_and_b32_e32 v76, 0xffff0000, v78
	v_pk_mul_f32 v[74:75], v[82:83], v[74:75] op_sel:[1,0] op_sel_hi:[0,1]
	v_pk_fma_f32 v[74:75], v[82:83], v[76:77], v[74:75]
	v_and_b32_e32 v71, 0xffff0000, v71
	v_and_b32_e32 v70, 0xffff0000, v70
	v_cvt_pk_bf16_f32 v69, v85, v69
	v_cvt_pk_bf16_f32 v68, v84, v68
	v_pk_fma_f32 v[70:71], v[80:81], v[70:71], v[74:75] op_sel_hi:[0,1,1]
	v_cvt_pk_bf16_f32 v70, v72, v70
	v_cvt_pk_bf16_f32 v71, v73, v71
	v_lshl_add_u64 v[72:73], v[88:89], 0, v[132:133]
	v_add_co_u32_e32 v72, vcc, s25, v72
	v_addc_co_u32_e32 v73, vcc, -1, v73, vcc
	global_store_dwordx4 v[72:73], v[68:71], off offset:-3072 sc1
	s_waitcnt vmcnt(25)
	v_lshlrev_b32_e32 v73, 16, v67
	v_lshlrev_b32_e32 v72, 16, v66
	v_lshlrev_b32_e32 v69, 16, v65
	v_lshlrev_b32_e32 v68, 16, v64
	s_waitcnt vmcnt(24)
	v_lshlrev_b32_e32 v71, 16, v61
	v_lshlrev_b32_e32 v70, 16, v60
	v_and_b32_e32 v65, 0xffff0000, v65
	v_and_b32_e32 v64, 0xffff0000, v64
	v_and_b32_e32 v61, 0xffff0000, v61
	v_and_b32_e32 v60, 0xffff0000, v60
	v_pk_fma_f32 v[68:69], v[122:123], v[70:71], v[68:69] neg_lo:[1,0,0] neg_hi:[1,0,0]
	v_pk_fma_f32 v[60:61], v[122:123], v[60:61], v[64:65] neg_lo:[1,0,0] neg_hi:[1,0,0]
	v_pk_mul_f32 v[64:65], v[68:69], v[68:69]
	v_pk_mul_f32 v[70:71], v[60:61], v[60:61]
	v_lshlrev_b32_e32 v75, 16, v63
	v_lshlrev_b32_e32 v74, 16, v62
	v_and_b32_e32 v67, 0xffff0000, v67
	v_and_b32_e32 v66, 0xffff0000, v66
	v_and_b32_e32 v63, 0xffff0000, v63
	v_and_b32_e32 v62, 0xffff0000, v62
	v_pk_fma_f32 v[72:73], v[122:123], v[74:75], v[72:73] neg_lo:[1,0,0] neg_hi:[1,0,0]
	v_pk_fma_f32 v[62:63], v[122:123], v[62:63], v[66:67] neg_lo:[1,0,0] neg_hi:[1,0,0]
	v_add_f32_e32 v64, v64, v70
	v_mov_b32_e32 v66, v62
	v_mov_b32_e32 v67, v72
	v_add_f32_e32 v64, v65, v64
	v_pk_mul_f32 v[66:67], v[66:67], v[66:67]
	v_add_f32_e32 v64, v71, v64
	v_mov_b32_e32 v74, v63
	v_mov_b32_e32 v75, v73
	v_add_f32_e32 v64, v67, v64
	v_pk_mul_f32 v[74:75], v[74:75], v[74:75]
	v_add_f32_e32 v64, v66, v64
	v_add_f32_e32 v64, v75, v64
	v_add_f32_e32 v64, v74, v64
	v_lshl_add_u64 v[132:133], v[132:133], 0, s[8:9]
	s_waitcnt lgkmcnt(0)
	s_nop 1
	v_add_f32_dpp v64, v64, v64 quad_perm:[1,0,3,2] row_mask:0xf bank_mask:0xf
	s_waitcnt lgkmcnt(0)
	s_nop 1
	v_add_f32_dpp v64, v64, v64 quad_perm:[2,3,0,1] row_mask:0xf bank_mask:0xf
	s_waitcnt lgkmcnt(0)
	s_nop 1
	v_add_f32_dpp v64, v64, v64 row_half_mirror row_mask:0xf bank_mask:0xf
	s_waitcnt lgkmcnt(0)
	s_nop 1
	v_add_f32_dpp v64, v64, v64 row_mirror row_mask:0xf bank_mask:0xf
	v_fmamk_f32 v64, v64, 0x3c000000, v140
	v_cmp_gt_f32_e32 vcc, s21, v64
	v_mul_f32_e32 v65, 0x4f800000, v64
	s_nop 0
	v_cndmask_b32_e32 v64, v64, v65, vcc
	v_sqrt_f32_e32 v65, v64
	s_nop 0
	v_add_u32_e32 v66, -1, v65
	v_fma_f32 v67, -v66, v65, v64
	v_cmp_ge_f32_e64 s[0:1], 0, v67
	v_add_u32_e32 v67, 1, v65
	s_nop 0
	v_cndmask_b32_e64 v66, v65, v66, s[0:1]
	v_fma_f32 v65, -v67, v65, v64
	v_cmp_lt_f32_e64 s[0:1], 0, v65
	s_nop 1
	v_cndmask_b32_e64 v65, v66, v67, s[0:1]
	v_mul_f32_e32 v66, 0x37800000, v65
	v_cndmask_b32_e32 v65, v65, v66, vcc
	v_cmp_class_f32_e32 vcc, v64, v141
	s_nop 1
	v_cndmask_b32_e32 v64, v65, v64, vcc
	v_div_scale_f32 v65, s[0:1], v64, v64, s22
	v_rcp_f32_e32 v66, v65
	s_nop 0
	v_fma_f32 v67, -v65, v66, 1.0
	v_fmac_f32_e32 v66, v67, v66
	v_div_scale_f32 v67, vcc, s22, v64, s22
	v_mul_f32_e32 v70, v67, v66
	v_fma_f32 v71, -v65, v70, v67
	v_fmac_f32_e32 v70, v71, v66
	v_fma_f32 v65, -v65, v70, v67
	v_div_fmas_f32 v65, v65, v66, v70
	v_div_fixup_f32 v64, v65, v64, s22
	v_pk_mul_f32 v[62:63], v[62:63], v[64:65] op_sel_hi:[1,0]
	v_pk_mul_f32 v[66:67], v[68:69], v[64:65] op_sel_hi:[1,0]
	v_pk_mul_f32 v[62:63], v[4:5], v[62:63]
	v_pk_mul_f32 v[66:67], v[2:3], v[66:67]
	v_pk_mul_f32 v[60:61], v[60:61], v[64:65] op_sel_hi:[1,0]
	v_pk_mul_f32 v[68:69], v[72:73], v[64:65] op_sel_hi:[1,0]
	v_bfe_u32 v64, v63, 16, 1
	v_bfe_u32 v65, v62, 16, 1
	v_pk_mul_f32 v[60:61], v[124:125], v[60:61]
	v_add3_u32 v62, v62, v65, s23
	v_add3_u32 v63, v63, v64, s23
	v_cvt_pk_bf16_f32 v60, v66, v60
	v_cvt_pk_bf16_f32 v61, v67, v61
	v_pk_mul_f32 v[68:69], v[6:7], v[68:69]
	v_bfe_u32 v70, v68, 16, 1
	v_bfe_u32 v71, v69, 16, 1
	v_add3_u32 v69, v69, v71, s23
	v_add3_u32 v68, v68, v70, s23
	v_lshl_add_u64 v[64:65], v[100:101], 0, v[120:121]
	v_lshrrev_b32_e32 v66, 16, v68
	v_lshrrev_b32_e32 v67, 16, v69
	v_add_co_u32_e32 v64, vcc, s24, v64
	v_and_or_b32 v63, v63, s20, v67
	v_and_or_b32 v62, v62, s20, v66
	v_addc_co_u32_e32 v65, vcc, -1, v65, vcc
	global_store_dwordx4 v[64:65], v[60:63], off offset:-256 sc1
	v_lshl_add_u64 v[120:121], v[120:121], 0, s[8:9]
	s_waitcnt vmcnt(22)
	v_max3_f32 v60, v148, v149, v150
	v_sub_f32_e32 v61, v148, v60
	v_exp_f32_e32 v63, v61
	v_sub_f32_e32 v61, v149, v60
	v_exp_f32_e32 v62, v61
	v_sub_f32_e32 v60, v150, v60
	v_exp_f32_e32 v60, v60
	v_add_f32_e32 v61, v63, v62
	v_add_f32_e32 v61, v60, v61
	v_div_scale_f32 v64, s[0:1], v61, v61, 1.0
	v_rcp_f32_e32 v65, v64
	s_nop 0
	v_fma_f32 v66, -v64, v65, 1.0
	v_fmac_f32_e32 v65, v66, v65
	v_div_scale_f32 v66, vcc, 1.0, v61, 1.0
	v_mul_f32_e32 v67, v66, v65
	v_fma_f32 v68, -v64, v67, v66
	v_fmac_f32_e32 v67, v68, v65
	v_fma_f32 v64, -v64, v67, v66
	v_div_fmas_f32 v64, v64, v65, v67
	v_div_fixup_f32 v64, v64, v61, 1.0
	v_pk_mul_f32 v[62:63], v[62:63], v[64:65] op_sel_hi:[1,0]
	s_waitcnt vmcnt(20)
	v_lshlrev_b32_e32 v67, 16, v57
	v_lshlrev_b32_e32 v66, 16, v52
	v_mul_f32_e32 v60, v60, v64
	v_lshlrev_b32_e32 v65, 16, v53
	v_lshlrev_b32_e32 v64, 16, v56
	v_pk_mul_f32 v[66:67], v[62:63], v[66:67] op_sel:[1,0] op_sel_hi:[0,1]
	v_pk_fma_f32 v[64:65], v[62:63], v[64:65], v[66:67]
	s_waitcnt vmcnt(19)
	v_lshlrev_b32_e32 v67, 16, v49
	v_lshlrev_b32_e32 v66, 16, v48
	v_pk_fma_f32 v[64:65], v[60:61], v[66:67], v[64:65] op_sel_hi:[0,1,1]
	v_and_b32_e32 v67, 0xffff0000, v53
	v_and_b32_e32 v53, 0xffff0000, v57
	v_and_b32_e32 v52, 0xffff0000, v52
	v_and_b32_e32 v66, 0xffff0000, v56
	v_pk_mul_f32 v[52:53], v[62:63], v[52:53] op_sel:[1,0] op_sel_hi:[0,1]
	v_pk_fma_f32 v[52:53], v[62:63], v[66:67], v[52:53]
	v_and_b32_e32 v49, 0xffff0000, v49
	v_and_b32_e32 v48, 0xffff0000, v48
	v_lshlrev_b32_e32 v57, 16, v59
	v_lshlrev_b32_e32 v56, 16, v54
	v_pk_fma_f32 v[48:49], v[60:61], v[48:49], v[52:53] op_sel_hi:[0,1,1]
	v_lshlrev_b32_e32 v53, 16, v55
	v_lshlrev_b32_e32 v52, 16, v58
	v_pk_mul_f32 v[56:57], v[62:63], v[56:57] op_sel:[1,0] op_sel_hi:[0,1]
	v_pk_fma_f32 v[52:53], v[62:63], v[52:53], v[56:57]
	v_lshlrev_b32_e32 v57, 16, v51
	v_lshlrev_b32_e32 v56, 16, v50
	v_pk_fma_f32 v[52:53], v[60:61], v[56:57], v[52:53] op_sel_hi:[0,1,1]
	v_and_b32_e32 v57, 0xffff0000, v55
	v_and_b32_e32 v55, 0xffff0000, v59
	v_and_b32_e32 v54, 0xffff0000, v54
	v_and_b32_e32 v56, 0xffff0000, v58
	v_pk_mul_f32 v[54:55], v[62:63], v[54:55] op_sel:[1,0] op_sel_hi:[0,1]
	v_pk_fma_f32 v[54:55], v[62:63], v[56:57], v[54:55]
	v_and_b32_e32 v51, 0xffff0000, v51
	v_and_b32_e32 v50, 0xffff0000, v50
	v_cvt_pk_bf16_f32 v49, v65, v49
	v_cvt_pk_bf16_f32 v48, v64, v48
	v_pk_fma_f32 v[50:51], v[60:61], v[50:51], v[54:55] op_sel_hi:[0,1,1]
	v_cvt_pk_bf16_f32 v50, v52, v50
	v_cvt_pk_bf16_f32 v51, v53, v51
	v_lshl_add_u64 v[52:53], v[88:89], 0, v[118:119]
	v_add_co_u32_e32 v52, vcc, s25, v52
	v_addc_co_u32_e32 v53, vcc, -1, v53, vcc
	global_store_dwordx4 v[52:53], v[48:51], off offset:-3072 sc1
	s_waitcnt vmcnt(19)
	v_lshlrev_b32_e32 v53, 16, v47
	v_lshlrev_b32_e32 v52, 16, v46
	v_lshlrev_b32_e32 v49, 16, v45
	v_lshlrev_b32_e32 v48, 16, v44
	s_waitcnt vmcnt(18)
	v_lshlrev_b32_e32 v51, 16, v41
	v_lshlrev_b32_e32 v50, 16, v40
	v_and_b32_e32 v45, 0xffff0000, v45
	v_and_b32_e32 v44, 0xffff0000, v44
	v_and_b32_e32 v41, 0xffff0000, v41
	v_and_b32_e32 v40, 0xffff0000, v40
	v_pk_fma_f32 v[48:49], v[122:123], v[50:51], v[48:49] neg_lo:[1,0,0] neg_hi:[1,0,0]
	v_pk_fma_f32 v[40:41], v[122:123], v[40:41], v[44:45] neg_lo:[1,0,0] neg_hi:[1,0,0]
	v_pk_mul_f32 v[44:45], v[48:49], v[48:49]
	v_pk_mul_f32 v[50:51], v[40:41], v[40:41]
	v_lshlrev_b32_e32 v55, 16, v43
	v_lshlrev_b32_e32 v54, 16, v42
	v_and_b32_e32 v47, 0xffff0000, v47
	v_and_b32_e32 v46, 0xffff0000, v46
	v_and_b32_e32 v43, 0xffff0000, v43
	v_and_b32_e32 v42, 0xffff0000, v42
	v_pk_fma_f32 v[52:53], v[122:123], v[54:55], v[52:53] neg_lo:[1,0,0] neg_hi:[1,0,0]
	v_pk_fma_f32 v[42:43], v[122:123], v[42:43], v[46:47] neg_lo:[1,0,0] neg_hi:[1,0,0]
	v_add_f32_e32 v44, v44, v50
	v_mov_b32_e32 v46, v42
	v_mov_b32_e32 v47, v52
	v_add_f32_e32 v44, v45, v44
	v_pk_mul_f32 v[46:47], v[46:47], v[46:47]
	v_add_f32_e32 v44, v51, v44
	v_mov_b32_e32 v54, v43
	v_mov_b32_e32 v55, v53
	v_add_f32_e32 v44, v47, v44
	v_pk_mul_f32 v[54:55], v[54:55], v[54:55]
	v_add_f32_e32 v44, v46, v44
	v_add_f32_e32 v44, v55, v44
	v_add_f32_e32 v44, v54, v44
	v_lshl_add_u64 v[118:119], v[118:119], 0, s[8:9]
	s_waitcnt lgkmcnt(0)
	s_nop 1
	v_add_f32_dpp v44, v44, v44 quad_perm:[1,0,3,2] row_mask:0xf bank_mask:0xf
	s_waitcnt lgkmcnt(0)
	s_nop 1
	v_add_f32_dpp v44, v44, v44 quad_perm:[2,3,0,1] row_mask:0xf bank_mask:0xf
	s_waitcnt lgkmcnt(0)
	s_nop 1
	v_add_f32_dpp v44, v44, v44 row_half_mirror row_mask:0xf bank_mask:0xf
	s_waitcnt lgkmcnt(0)
	s_nop 1
	v_add_f32_dpp v44, v44, v44 row_mirror row_mask:0xf bank_mask:0xf
	v_fmamk_f32 v44, v44, 0x3c000000, v140
	v_cmp_gt_f32_e32 vcc, s21, v44
	v_mul_f32_e32 v45, 0x4f800000, v44
	s_nop 0
	v_cndmask_b32_e32 v44, v44, v45, vcc
	v_sqrt_f32_e32 v45, v44
	s_nop 0
	v_add_u32_e32 v46, -1, v45
	v_fma_f32 v47, -v46, v45, v44
	v_cmp_ge_f32_e64 s[0:1], 0, v47
	v_add_u32_e32 v47, 1, v45
	s_nop 0
	v_cndmask_b32_e64 v46, v45, v46, s[0:1]
	v_fma_f32 v45, -v47, v45, v44
	v_cmp_lt_f32_e64 s[0:1], 0, v45
	s_nop 1
	v_cndmask_b32_e64 v45, v46, v47, s[0:1]
	v_mul_f32_e32 v46, 0x37800000, v45
	v_cndmask_b32_e32 v45, v45, v46, vcc
	v_cmp_class_f32_e32 vcc, v44, v141
	s_nop 1
	v_cndmask_b32_e32 v44, v45, v44, vcc
	v_div_scale_f32 v45, s[0:1], v44, v44, s22
	v_rcp_f32_e32 v46, v45
	s_nop 0
	v_fma_f32 v47, -v45, v46, 1.0
	v_fmac_f32_e32 v46, v47, v46
	v_div_scale_f32 v47, vcc, s22, v44, s22
	v_mul_f32_e32 v50, v47, v46
	v_fma_f32 v51, -v45, v50, v47
	v_fmac_f32_e32 v50, v51, v46
	v_fma_f32 v45, -v45, v50, v47
	v_div_fmas_f32 v45, v45, v46, v50
	v_div_fixup_f32 v44, v45, v44, s22
	v_pk_mul_f32 v[42:43], v[42:43], v[44:45] op_sel_hi:[1,0]
	v_pk_mul_f32 v[46:47], v[48:49], v[44:45] op_sel_hi:[1,0]
	v_pk_mul_f32 v[42:43], v[4:5], v[42:43]
	v_pk_mul_f32 v[46:47], v[2:3], v[46:47]
	v_pk_mul_f32 v[40:41], v[40:41], v[44:45] op_sel_hi:[1,0]
	v_pk_mul_f32 v[48:49], v[52:53], v[44:45] op_sel_hi:[1,0]
	v_bfe_u32 v44, v43, 16, 1
	v_bfe_u32 v45, v42, 16, 1
	v_pk_mul_f32 v[40:41], v[124:125], v[40:41]
	v_add3_u32 v42, v42, v45, s23
	v_add3_u32 v43, v43, v44, s23
	v_cvt_pk_bf16_f32 v40, v46, v40
	v_cvt_pk_bf16_f32 v41, v47, v41
	v_pk_mul_f32 v[48:49], v[6:7], v[48:49]
	v_bfe_u32 v50, v48, 16, 1
	v_bfe_u32 v51, v49, 16, 1
	v_add3_u32 v49, v49, v51, s23
	v_add3_u32 v48, v48, v50, s23
	v_lshl_add_u64 v[44:45], v[100:101], 0, v[110:111]
	v_lshrrev_b32_e32 v46, 16, v48
	v_lshrrev_b32_e32 v47, 16, v49
	v_add_co_u32_e32 v44, vcc, s24, v44
	v_and_or_b32 v43, v43, s20, v47
	v_and_or_b32 v42, v42, s20, v46
	v_addc_co_u32_e32 v45, vcc, -1, v45, vcc
	global_store_dwordx4 v[44:45], v[40:43], off offset:-256 sc1
	v_lshl_add_u64 v[110:111], v[110:111], 0, s[8:9]
	s_waitcnt vmcnt(16)
	v_max3_f32 v40, v145, v146, v147
	v_sub_f32_e32 v41, v145, v40
	v_exp_f32_e32 v43, v41
	v_sub_f32_e32 v41, v146, v40
	v_exp_f32_e32 v42, v41
	v_sub_f32_e32 v40, v147, v40
	v_exp_f32_e32 v40, v40
	v_add_f32_e32 v41, v43, v42
	v_add_f32_e32 v41, v40, v41
	v_div_scale_f32 v44, s[0:1], v41, v41, 1.0
	v_rcp_f32_e32 v45, v44
	s_nop 0
	v_fma_f32 v46, -v44, v45, 1.0
	v_fmac_f32_e32 v45, v46, v45
	v_div_scale_f32 v46, vcc, 1.0, v41, 1.0
	v_mul_f32_e32 v47, v46, v45
	v_fma_f32 v48, -v44, v47, v46
	v_fmac_f32_e32 v47, v48, v45
	v_fma_f32 v44, -v44, v47, v46
	v_div_fmas_f32 v44, v44, v45, v47
	v_div_fixup_f32 v44, v44, v41, 1.0
	v_pk_mul_f32 v[42:43], v[42:43], v[44:45] op_sel_hi:[1,0]
	s_waitcnt vmcnt(14)
	v_lshlrev_b32_e32 v47, 16, v37
	v_lshlrev_b32_e32 v46, 16, v32
	v_mul_f32_e32 v40, v40, v44
	v_lshlrev_b32_e32 v45, 16, v33
	v_lshlrev_b32_e32 v44, 16, v36
	v_pk_mul_f32 v[46:47], v[42:43], v[46:47] op_sel:[1,0] op_sel_hi:[0,1]
	v_pk_fma_f32 v[44:45], v[42:43], v[44:45], v[46:47]
	s_waitcnt vmcnt(13)
	v_lshlrev_b32_e32 v47, 16, v29
	v_lshlrev_b32_e32 v46, 16, v28
	v_pk_fma_f32 v[44:45], v[40:41], v[46:47], v[44:45] op_sel_hi:[0,1,1]
	v_and_b32_e32 v47, 0xffff0000, v33
	v_and_b32_e32 v33, 0xffff0000, v37
	v_and_b32_e32 v32, 0xffff0000, v32
	v_and_b32_e32 v46, 0xffff0000, v36
	v_pk_mul_f32 v[32:33], v[42:43], v[32:33] op_sel:[1,0] op_sel_hi:[0,1]
	v_pk_fma_f32 v[32:33], v[42:43], v[46:47], v[32:33]
	v_and_b32_e32 v29, 0xffff0000, v29
	v_and_b32_e32 v28, 0xffff0000, v28
	v_lshlrev_b32_e32 v37, 16, v39
	v_lshlrev_b32_e32 v36, 16, v34
	v_pk_fma_f32 v[28:29], v[40:41], v[28:29], v[32:33] op_sel_hi:[0,1,1]
	v_lshlrev_b32_e32 v33, 16, v35
	v_lshlrev_b32_e32 v32, 16, v38
	v_pk_mul_f32 v[36:37], v[42:43], v[36:37] op_sel:[1,0] op_sel_hi:[0,1]
	v_pk_fma_f32 v[32:33], v[42:43], v[32:33], v[36:37]
	v_lshlrev_b32_e32 v37, 16, v31
	v_lshlrev_b32_e32 v36, 16, v30
	v_pk_fma_f32 v[32:33], v[40:41], v[36:37], v[32:33] op_sel_hi:[0,1,1]
	v_and_b32_e32 v37, 0xffff0000, v35
	v_and_b32_e32 v35, 0xffff0000, v39
	v_and_b32_e32 v34, 0xffff0000, v34
	v_and_b32_e32 v36, 0xffff0000, v38
	v_pk_mul_f32 v[34:35], v[42:43], v[34:35] op_sel:[1,0] op_sel_hi:[0,1]
	v_pk_fma_f32 v[34:35], v[42:43], v[36:37], v[34:35]
	v_and_b32_e32 v31, 0xffff0000, v31
	v_and_b32_e32 v30, 0xffff0000, v30
	v_cvt_pk_bf16_f32 v29, v45, v29
	v_cvt_pk_bf16_f32 v28, v44, v28
	v_pk_fma_f32 v[30:31], v[40:41], v[30:31], v[34:35] op_sel_hi:[0,1,1]
	v_cvt_pk_bf16_f32 v30, v32, v30
	v_cvt_pk_bf16_f32 v31, v33, v31
	v_lshl_add_u64 v[32:33], v[88:89], 0, v[108:109]
	v_add_co_u32_e32 v32, vcc, s25, v32
	v_addc_co_u32_e32 v33, vcc, -1, v33, vcc
	global_store_dwordx4 v[32:33], v[28:31], off offset:-3072 sc1
	s_waitcnt vmcnt(13)
	v_lshlrev_b32_e32 v33, 16, v27
	v_lshlrev_b32_e32 v32, 16, v26
	v_lshlrev_b32_e32 v29, 16, v25
	v_lshlrev_b32_e32 v28, 16, v24
	s_waitcnt vmcnt(12)
	v_lshlrev_b32_e32 v31, 16, v21
	v_lshlrev_b32_e32 v30, 16, v20
	v_and_b32_e32 v25, 0xffff0000, v25
	v_and_b32_e32 v24, 0xffff0000, v24
	v_and_b32_e32 v21, 0xffff0000, v21
	v_and_b32_e32 v20, 0xffff0000, v20
	v_pk_fma_f32 v[28:29], v[122:123], v[30:31], v[28:29] neg_lo:[1,0,0] neg_hi:[1,0,0]
	v_pk_fma_f32 v[20:21], v[122:123], v[20:21], v[24:25] neg_lo:[1,0,0] neg_hi:[1,0,0]
	v_pk_mul_f32 v[24:25], v[28:29], v[28:29]
	v_pk_mul_f32 v[30:31], v[20:21], v[20:21]
	v_lshlrev_b32_e32 v35, 16, v23
	v_lshlrev_b32_e32 v34, 16, v22
	v_and_b32_e32 v27, 0xffff0000, v27
	v_and_b32_e32 v26, 0xffff0000, v26
	v_and_b32_e32 v23, 0xffff0000, v23
	v_and_b32_e32 v22, 0xffff0000, v22
	v_pk_fma_f32 v[32:33], v[122:123], v[34:35], v[32:33] neg_lo:[1,0,0] neg_hi:[1,0,0]
	v_pk_fma_f32 v[22:23], v[122:123], v[22:23], v[26:27] neg_lo:[1,0,0] neg_hi:[1,0,0]
	v_add_f32_e32 v24, v24, v30
	v_mov_b32_e32 v26, v22
	v_mov_b32_e32 v27, v32
	v_add_f32_e32 v24, v25, v24
	v_pk_mul_f32 v[26:27], v[26:27], v[26:27]
	v_add_f32_e32 v24, v31, v24
	v_mov_b32_e32 v34, v23
	v_mov_b32_e32 v35, v33
	v_add_f32_e32 v24, v27, v24
	v_pk_mul_f32 v[34:35], v[34:35], v[34:35]
	v_add_f32_e32 v24, v26, v24
	v_add_f32_e32 v24, v35, v24
	v_add_f32_e32 v24, v34, v24
	v_lshl_add_u64 v[108:109], v[108:109], 0, s[8:9]
	s_waitcnt lgkmcnt(0)
	s_nop 1
	v_add_f32_dpp v24, v24, v24 quad_perm:[1,0,3,2] row_mask:0xf bank_mask:0xf
	s_waitcnt lgkmcnt(0)
	s_nop 1
	v_add_f32_dpp v24, v24, v24 quad_perm:[2,3,0,1] row_mask:0xf bank_mask:0xf
	s_waitcnt lgkmcnt(0)
	s_nop 1
	v_add_f32_dpp v24, v24, v24 row_half_mirror row_mask:0xf bank_mask:0xf
	s_waitcnt lgkmcnt(0)
	s_nop 1
	v_add_f32_dpp v24, v24, v24 row_mirror row_mask:0xf bank_mask:0xf
	v_fmamk_f32 v24, v24, 0x3c000000, v140
	v_cmp_gt_f32_e32 vcc, s21, v24
	v_mul_f32_e32 v25, 0x4f800000, v24
	s_nop 0
	v_cndmask_b32_e32 v24, v24, v25, vcc
	v_sqrt_f32_e32 v25, v24
	s_nop 0
	v_add_u32_e32 v26, -1, v25
	v_fma_f32 v27, -v26, v25, v24
	v_cmp_ge_f32_e64 s[0:1], 0, v27
	v_add_u32_e32 v27, 1, v25
	s_nop 0
	v_cndmask_b32_e64 v26, v25, v26, s[0:1]
	v_fma_f32 v25, -v27, v25, v24
	v_cmp_lt_f32_e64 s[0:1], 0, v25
	s_nop 1
	v_cndmask_b32_e64 v25, v26, v27, s[0:1]
	v_mul_f32_e32 v26, 0x37800000, v25
	v_cndmask_b32_e32 v25, v25, v26, vcc
	v_cmp_class_f32_e32 vcc, v24, v141
	s_nop 1
	v_cndmask_b32_e32 v24, v25, v24, vcc
	v_div_scale_f32 v25, s[0:1], v24, v24, s22
	v_rcp_f32_e32 v26, v25
	s_nop 0
	v_fma_f32 v27, -v25, v26, 1.0
	v_fmac_f32_e32 v26, v27, v26
	v_div_scale_f32 v27, vcc, s22, v24, s22
	v_mul_f32_e32 v30, v27, v26
	v_fma_f32 v31, -v25, v30, v27
	v_fmac_f32_e32 v30, v31, v26
	v_fma_f32 v25, -v25, v30, v27
	v_div_fmas_f32 v25, v25, v26, v30
	v_div_fixup_f32 v24, v25, v24, s22
	v_pk_mul_f32 v[22:23], v[22:23], v[24:25] op_sel_hi:[1,0]
	v_pk_mul_f32 v[26:27], v[28:29], v[24:25] op_sel_hi:[1,0]
	v_pk_mul_f32 v[22:23], v[4:5], v[22:23]
	v_pk_mul_f32 v[26:27], v[2:3], v[26:27]
	v_pk_mul_f32 v[20:21], v[20:21], v[24:25] op_sel_hi:[1,0]
	v_pk_mul_f32 v[28:29], v[32:33], v[24:25] op_sel_hi:[1,0]
	v_bfe_u32 v24, v23, 16, 1
	v_bfe_u32 v25, v22, 16, 1
	v_pk_mul_f32 v[20:21], v[124:125], v[20:21]
	v_add3_u32 v22, v22, v25, s23
	v_add3_u32 v23, v23, v24, s23
	v_cvt_pk_bf16_f32 v20, v26, v20
	v_cvt_pk_bf16_f32 v21, v27, v21
	v_pk_mul_f32 v[28:29], v[6:7], v[28:29]
	v_bfe_u32 v30, v28, 16, 1
	v_bfe_u32 v31, v29, 16, 1
	v_add3_u32 v29, v29, v31, s23
	v_add3_u32 v28, v28, v30, s23
	v_lshl_add_u64 v[24:25], v[100:101], 0, v[98:99]
	v_lshrrev_b32_e32 v26, 16, v28
	v_lshrrev_b32_e32 v27, 16, v29
	v_add_co_u32_e32 v24, vcc, s24, v24
	v_and_or_b32 v23, v23, s20, v27
	v_and_or_b32 v22, v22, s20, v26
	v_addc_co_u32_e32 v25, vcc, -1, v25, vcc
	global_store_dwordx4 v[24:25], v[20:23], off offset:-256 sc1
	v_lshl_add_u64 v[98:99], v[98:99], 0, s[8:9]
	s_waitcnt vmcnt(10)
	v_max3_f32 v20, v142, v143, v144
	v_sub_f32_e32 v21, v142, v20
	v_exp_f32_e32 v23, v21
	v_sub_f32_e32 v21, v143, v20
	v_exp_f32_e32 v22, v21
	v_sub_f32_e32 v20, v144, v20
	v_exp_f32_e32 v20, v20
	v_add_f32_e32 v21, v23, v22
	v_add_f32_e32 v21, v20, v21
	v_div_scale_f32 v24, s[0:1], v21, v21, 1.0
	v_rcp_f32_e32 v25, v24
	s_nop 0
	v_fma_f32 v26, -v24, v25, 1.0
	v_fmac_f32_e32 v25, v26, v25
	v_div_scale_f32 v26, vcc, 1.0, v21, 1.0
	v_mul_f32_e32 v27, v26, v25
	v_fma_f32 v28, -v24, v27, v26
	v_fmac_f32_e32 v27, v28, v25
	v_fma_f32 v24, -v24, v27, v26
	v_div_fmas_f32 v24, v24, v25, v27
	v_div_fixup_f32 v24, v24, v21, 1.0
	v_pk_mul_f32 v[22:23], v[22:23], v[24:25] op_sel_hi:[1,0]
	s_waitcnt vmcnt(8)
	v_lshlrev_b32_e32 v27, 16, v17
	v_lshlrev_b32_e32 v26, 16, v12
	v_mul_f32_e32 v20, v20, v24
	v_lshlrev_b32_e32 v25, 16, v13
	v_lshlrev_b32_e32 v24, 16, v16
	v_pk_mul_f32 v[26:27], v[22:23], v[26:27] op_sel:[1,0] op_sel_hi:[0,1]
	v_pk_fma_f32 v[24:25], v[22:23], v[24:25], v[26:27]
	s_waitcnt vmcnt(7)
	v_lshlrev_b32_e32 v27, 16, v9
	v_lshlrev_b32_e32 v26, 16, v8
	v_pk_fma_f32 v[24:25], v[20:21], v[26:27], v[24:25] op_sel_hi:[0,1,1]
	v_and_b32_e32 v27, 0xffff0000, v13
	v_and_b32_e32 v13, 0xffff0000, v17
	v_and_b32_e32 v12, 0xffff0000, v12
	v_and_b32_e32 v26, 0xffff0000, v16
	v_pk_mul_f32 v[12:13], v[22:23], v[12:13] op_sel:[1,0] op_sel_hi:[0,1]
	v_pk_fma_f32 v[12:13], v[22:23], v[26:27], v[12:13]
	v_and_b32_e32 v9, 0xffff0000, v9
	v_and_b32_e32 v8, 0xffff0000, v8
	v_lshlrev_b32_e32 v17, 16, v19
	v_lshlrev_b32_e32 v16, 16, v14
	v_pk_fma_f32 v[8:9], v[20:21], v[8:9], v[12:13] op_sel_hi:[0,1,1]
	v_lshlrev_b32_e32 v13, 16, v15
	v_lshlrev_b32_e32 v12, 16, v18
	v_pk_mul_f32 v[16:17], v[22:23], v[16:17] op_sel:[1,0] op_sel_hi:[0,1]
	v_pk_fma_f32 v[12:13], v[22:23], v[12:13], v[16:17]
	v_lshlrev_b32_e32 v17, 16, v11
	v_lshlrev_b32_e32 v16, 16, v10
	v_pk_fma_f32 v[12:13], v[20:21], v[16:17], v[12:13] op_sel_hi:[0,1,1]
	v_and_b32_e32 v17, 0xffff0000, v15
	v_and_b32_e32 v15, 0xffff0000, v19
	v_and_b32_e32 v14, 0xffff0000, v14
	v_and_b32_e32 v16, 0xffff0000, v18
	v_pk_mul_f32 v[14:15], v[22:23], v[14:15] op_sel:[1,0] op_sel_hi:[0,1]
	v_pk_fma_f32 v[14:15], v[22:23], v[16:17], v[14:15]
	v_and_b32_e32 v11, 0xffff0000, v11
	v_and_b32_e32 v10, 0xffff0000, v10
	v_cvt_pk_bf16_f32 v9, v25, v9
	v_cvt_pk_bf16_f32 v8, v24, v8
	v_pk_fma_f32 v[10:11], v[20:21], v[10:11], v[14:15] op_sel_hi:[0,1,1]
	v_cvt_pk_bf16_f32 v10, v12, v10
	v_cvt_pk_bf16_f32 v11, v13, v11
	v_lshl_add_u64 v[12:13], v[88:89], 0, v[96:97]
	v_add_co_u32_e32 v12, vcc, s25, v12
	v_addc_co_u32_e32 v13, vcc, -1, v13, vcc
	v_lshl_add_u64 v[96:97], v[96:97], 0, s[8:9]
	global_store_dwordx4 v[12:13], v[8:11], off offset:-3072 sc1
	s_cbranch_scc1 .LBB0_495
